# row-phase modulation-vector prologues: both iterations' loads issued before one wait (loop unrolled)
# baseline (speedup 1.0000x reference)
; __device__ __forceinline__ float mod_val(const float* modp, const float* adab, int l, int b, int j) {
;     float s = adab[l * 3072 + j];
; #pragma unroll
;     for (int kc = 0; kc < KS; ++kc) s += modp[((size_t)(kc * 2 + l) * 8 + b) * 3072 + j];
;     return s;
; __device__ __forceinline__ void p1a_rows(const Args& A, char* lds, int G) {
;     ...
;         __syncthreads();
; #pragma unroll 1
;         for (int col = tid; col < 1024; col += NTHR) { mv[col] = A.in[I_PREG][col] * (1.f + mod_val(modp, A.in[I_ADAB], 0, b, 1024 + col)); mv[1024 + col] = mod_val(modp, A.in[I_ADAB], 0, b, col); }
;         __syncthreads();
.LBB0_385:
	v_lshl_add_u64 v[8:9], v[70:71], 0, s[10:11]
	v_lshl_add_u64 v[10:11], v[0:1], 0, s[10:11]
	flat_load_dword v24, v[8:9]
	flat_load_dword v25, v[10:11]
	v_add_co_u32_e32 v8, vcc, 0x30000, v10
	v_lshl_add_u64 v[6:7], v[76:77], 0, s[10:11]
	s_nop 0
	v_addc_co_u32_e32 v9, vcc, 0, v11, vcc
	v_add_co_u32_e32 v12, vcc, 0x60000, v10
	flat_load_dword v26, v[8:9]
	s_nop 0
	v_addc_co_u32_e32 v13, vcc, 0, v11, vcc
	v_add_co_u32_e32 v8, vcc, 0x90000, v10
	v_add_u32_e32 v5, 0x200, v5
	s_nop 0
	v_addc_co_u32_e32 v9, vcc, 0, v11, vcc
	v_add_co_u32_e32 v14, vcc, 0xc0000, v10
	flat_load_dword v27, v[12:13]
	flat_load_dword v28, v[8:9]
	v_addc_co_u32_e32 v15, vcc, 0, v11, vcc
	v_add_co_u32_e32 v8, vcc, 0xf0000, v10
	s_nop 0
	s_nop 0
	v_addc_co_u32_e32 v9, vcc, 0, v11, vcc
	v_add_co_u32_e32 v12, vcc, 0x120000, v10
	flat_load_dword v29, v[14:15]
	flat_load_dword v30, v[8:9]
	v_addc_co_u32_e32 v13, vcc, 0, v11, vcc
	v_add_co_u32_e32 v8, vcc, 0x150000, v10
	s_nop 0
	s_nop 0
	v_addc_co_u32_e32 v9, vcc, 0, v11, vcc
	flat_load_dword v31, v[12:13]
	flat_load_dword v32, v[8:9]
	flat_load_dword v33, v[6:7]
	v_lshl_add_u64 v[8:9], v[2:3], 0, s[10:11]
	v_add_co_u32_e32 v10, vcc, s1, v8
	s_nop 0
	s_nop 0
	v_addc_co_u32_e32 v11, vcc, 0, v9, vcc
	v_add_co_u32_e32 v12, vcc, s3, v8
	s_nop 0
	s_nop 0
	v_addc_co_u32_e32 v13, vcc, 0, v9, vcc
	v_add_co_u32_e32 v14, vcc, s12, v8
	v_lshl_add_u64 v[6:7], v[74:75], 0, s[10:11]
	s_nop 0
	v_addc_co_u32_e32 v15, vcc, 0, v9, vcc
	v_add_co_u32_e32 v16, vcc, s13, v8
	s_add_u32 s10, s10, 0x800
	s_nop 0
	v_addc_co_u32_e32 v17, vcc, 0, v9, vcc
	v_add_co_u32_e32 v18, vcc, s14, v8
	s_addc_u32 s11, s11, 0
	s_nop 0
	v_addc_co_u32_e32 v19, vcc, 0, v9, vcc
	v_add_co_u32_e32 v20, vcc, s15, v8
	s_nop 0
	s_nop 0
	s_nop 0
	v_addc_co_u32_e32 v21, vcc, 0, v9, vcc
	v_add_co_u32_e32 v22, vcc, s16, v8
	s_nop 0
	s_nop 0
	s_nop 0
	s_nop 0
	s_nop 0
	v_addc_co_u32_e32 v23, vcc, 0, v9, vcc
	flat_load_dword v34, v[6:7]
	flat_load_dword v35, v[8:9]
	flat_load_dword v36, v[10:11]
	flat_load_dword v37, v[12:13]
	flat_load_dword v38, v[14:15]
	flat_load_dword v39, v[16:17]
	flat_load_dword v40, v[18:19]
	flat_load_dword v41, v[20:21]
	flat_load_dword v42, v[22:23]
	v_cmp_lt_i32_e32 vcc, s17, v5
	s_or_b64 s[8:9], vcc, s[8:9]
	v_lshl_add_u64 v[8:9], v[70:71], 0, s[10:11]
	v_lshl_add_u64 v[10:11], v[0:1], 0, s[10:11]
	flat_load_dword v87, v[8:9]
	flat_load_dword v88, v[10:11]
	v_add_co_u32_e32 v8, vcc, 0x30000, v10
	v_lshl_add_u64 v[6:7], v[76:77], 0, s[10:11]
	s_nop 0
	v_addc_co_u32_e32 v9, vcc, 0, v11, vcc
	v_add_co_u32_e32 v12, vcc, 0x60000, v10
	flat_load_dword v89, v[8:9]
	s_nop 0
	v_addc_co_u32_e32 v13, vcc, 0, v11, vcc
	v_add_co_u32_e32 v8, vcc, 0x90000, v10
	v_add_u32_e32 v5, 0x200, v5
	s_nop 0
	v_addc_co_u32_e32 v9, vcc, 0, v11, vcc
	v_add_co_u32_e32 v14, vcc, 0xc0000, v10
	flat_load_dword v90, v[12:13]
	flat_load_dword v91, v[8:9]
	v_addc_co_u32_e32 v15, vcc, 0, v11, vcc
	v_add_co_u32_e32 v8, vcc, 0xf0000, v10
	s_nop 0
	s_nop 0
	v_addc_co_u32_e32 v9, vcc, 0, v11, vcc
	v_add_co_u32_e32 v12, vcc, 0x120000, v10
	flat_load_dword v92, v[14:15]
	flat_load_dword v93, v[8:9]
	v_addc_co_u32_e32 v13, vcc, 0, v11, vcc
	v_add_co_u32_e32 v8, vcc, 0x150000, v10
	s_nop 0
	s_nop 0
	v_addc_co_u32_e32 v9, vcc, 0, v11, vcc
	flat_load_dword v94, v[12:13]
	flat_load_dword v95, v[8:9]
	flat_load_dword v96, v[6:7]
	v_lshl_add_u64 v[8:9], v[2:3], 0, s[10:11]
	v_add_co_u32_e32 v10, vcc, s1, v8
	s_nop 0
	s_nop 0
	v_addc_co_u32_e32 v11, vcc, 0, v9, vcc
	v_add_co_u32_e32 v12, vcc, s3, v8
	s_nop 0
	s_nop 0
	v_addc_co_u32_e32 v13, vcc, 0, v9, vcc
	v_add_co_u32_e32 v14, vcc, s12, v8
	v_lshl_add_u64 v[6:7], v[74:75], 0, s[10:11]
	s_nop 0
	v_addc_co_u32_e32 v15, vcc, 0, v9, vcc
	v_add_co_u32_e32 v16, vcc, s13, v8
	s_add_u32 s10, s10, 0x800
	s_nop 0
	v_addc_co_u32_e32 v17, vcc, 0, v9, vcc
	v_add_co_u32_e32 v18, vcc, s14, v8
	s_addc_u32 s11, s11, 0
	s_nop 0
	v_addc_co_u32_e32 v19, vcc, 0, v9, vcc
	v_add_co_u32_e32 v20, vcc, s15, v8
	s_nop 0
	s_nop 0
	s_nop 0
	v_addc_co_u32_e32 v21, vcc, 0, v9, vcc
	v_add_co_u32_e32 v22, vcc, s16, v8
	s_nop 0
	s_nop 0
	s_nop 0
	s_nop 0
	s_nop 0
	v_addc_co_u32_e32 v23, vcc, 0, v9, vcc
	flat_load_dword v97, v[6:7]
	flat_load_dword v98, v[8:9]
	flat_load_dword v99, v[10:11]
	flat_load_dword v100, v[12:13]
	flat_load_dword v101, v[14:15]
	flat_load_dword v102, v[16:17]
	flat_load_dword v103, v[18:19]
	flat_load_dword v104, v[20:21]
	flat_load_dword v105, v[22:23]
	v_cmp_lt_i32_e32 vcc, s17, v5
	s_or_b64 s[8:9], vcc, s[8:9]
	s_waitcnt vmcnt(0) lgkmcnt(0)
	v_add_f32_e32 v24, v24, v25
	v_add_f32_e32 v24, v24, v26
	v_add_f32_e32 v24, v24, v27
	v_add_f32_e32 v24, v24, v28
	v_add_f32_e32 v24, v24, v29
	v_add_f32_e32 v24, v24, v30
	v_add_f32_e32 v24, v24, v31
	v_add_f32_e32 v24, v24, v32
	v_add_f32_e32 v24, 1.0, v24
	v_mul_f32_e32 v24, v33, v24
	ds_write_b32 v4, v24
	v_add_f32_e32 v6, v34, v35
	v_add_f32_e32 v6, v6, v36
	v_add_f32_e32 v6, v6, v37
	v_add_f32_e32 v6, v6, v38
	v_add_f32_e32 v6, v6, v39
	v_add_f32_e32 v6, v6, v40
	v_add_f32_e32 v6, v6, v41
	v_add_f32_e32 v6, v6, v42
	ds_write_b32 v4, v6 offset:4096
	v_add_u32_e32 v4, 0x800, v4
	v_add_f32_e32 v87, v87, v88
	v_add_f32_e32 v87, v87, v89
	v_add_f32_e32 v87, v87, v90
	v_add_f32_e32 v87, v87, v91
	v_add_f32_e32 v87, v87, v92
	v_add_f32_e32 v87, v87, v93
	v_add_f32_e32 v87, v87, v94
	v_add_f32_e32 v87, v87, v95
	v_add_f32_e32 v87, 1.0, v87
	v_mul_f32_e32 v87, v96, v87
	ds_write_b32 v4, v87
	v_add_f32_e32 v6, v97, v98
	v_add_f32_e32 v6, v6, v99
	v_add_f32_e32 v6, v6, v100
	v_add_f32_e32 v6, v6, v101
	v_add_f32_e32 v6, v6, v102
	v_add_f32_e32 v6, v6, v103
	v_add_f32_e32 v6, v6, v104
	v_add_f32_e32 v6, v6, v105
	ds_write_b32 v4, v6 offset:4096
	v_add_u32_e32 v4, 0x800, v4

; __device__ __forceinline__ float mod_val(const float* modp, const float* adab, int l, int b, int j) {
;     float s = adab[l * 3072 + j];
; #pragma unroll
;     for (int kc = 0; kc < KS; ++kc) s += modp[((size_t)(kc * 2 + l) * 8 + b) * 3072 + j];
;     return s;
; __device__ __forceinline__ void p3b_rows(const Args& A, char* lds, int G) {
;     ...
;         for (int col = tid; col < 1024; col += NTHR) { mv[col] = A.in[I_POSTG][col] * mod_val(modp, A.in[I_ADAB], 0, b, 2048 + col);
;             mv[1024 + col] = A.in[I_PREG][1024 + col] * (1.f + mod_val(modp, A.in[I_ADAB], 1, b, 1024 + col)); mv[2048 + col] = mod_val(modp, A.in[I_ADAB], 1, b, col); }
.LBB0_1173:
	v_lshl_add_u64 v[10:11], v[94:95], 0, s[16:17]
	v_lshl_add_u64 v[12:13], v[2:3], 0, s[16:17]
	flat_load_dword v30, v[10:11]
	flat_load_dword v31, v[12:13]
	v_add_co_u32_e32 v10, vcc, 0x30000, v12
	v_lshl_add_u64 v[8:9], v[100:101], 0, s[16:17]
	s_nop 0
	v_addc_co_u32_e32 v11, vcc, 0, v13, vcc
	v_add_co_u32_e32 v14, vcc, 0x60000, v12
	flat_load_dword v32, v[10:11]
	s_nop 0
	v_addc_co_u32_e32 v15, vcc, 0, v13, vcc
	v_add_co_u32_e32 v10, vcc, 0x90000, v12
	v_add_u32_e32 v7, 0x200, v7
	s_nop 0
	v_addc_co_u32_e32 v11, vcc, 0, v13, vcc
	v_add_co_u32_e32 v16, vcc, 0xc0000, v12
	flat_load_dword v33, v[14:15]
	flat_load_dword v34, v[10:11]
	v_addc_co_u32_e32 v17, vcc, 0, v13, vcc
	v_add_co_u32_e32 v10, vcc, 0xf0000, v12
	s_nop 0
	s_nop 0
	v_addc_co_u32_e32 v11, vcc, 0, v13, vcc
	v_add_co_u32_e32 v14, vcc, 0x120000, v12
	flat_load_dword v35, v[16:17]
	flat_load_dword v36, v[10:11]
	v_addc_co_u32_e32 v15, vcc, 0, v13, vcc
	v_add_co_u32_e32 v10, vcc, 0x150000, v12
	s_nop 0
	s_nop 0
	v_addc_co_u32_e32 v11, vcc, 0, v13, vcc
	flat_load_dword v37, v[14:15]
	flat_load_dword v38, v[10:11]
	flat_load_dword v39, v[8:9]
	v_lshl_add_u64 v[10:11], v[98:99], 0, s[16:17]
	v_add_co_u32_e32 v14, vcc, 0x4000, v10
	v_lshl_add_u64 v[12:13], v[0:1], 0, s[16:17]
	s_nop 0
	v_addc_co_u32_e32 v15, vcc, 0, v11, vcc
	v_add_co_u32_e32 v16, vcc, 0x18000, v12
	s_nop 0
	s_nop 0
	v_addc_co_u32_e32 v17, vcc, 0, v13, vcc
	v_add_co_u32_e32 v18, vcc, 0x48000, v12
	s_nop 0
	s_nop 0
	v_addc_co_u32_e32 v19, vcc, 0, v13, vcc
	v_add_co_u32_e32 v20, vcc, 0x78000, v12
	v_lshl_add_u64 v[8:9], v[90:91], 0, s[16:17]
	s_nop 0
	v_addc_co_u32_e32 v21, vcc, 0, v13, vcc
	v_add_co_u32_e32 v22, vcc, 0xa8000, v12
	s_nop 0
	s_nop 0
	v_addc_co_u32_e32 v23, vcc, 0, v13, vcc
	v_add_co_u32_e32 v24, vcc, 0xd8000, v12
	s_nop 0
	s_nop 0
	v_addc_co_u32_e32 v25, vcc, 0, v13, vcc
	v_add_co_u32_e32 v26, vcc, 0x108000, v12
	s_nop 0
	s_nop 0
	v_addc_co_u32_e32 v27, vcc, 0, v13, vcc
	v_add_co_u32_e32 v28, vcc, 0x138000, v12
	s_nop 0
	s_nop 0
	v_addc_co_u32_e32 v29, vcc, 0, v13, vcc
	s_nop 0
	v_add_co_u32_e32 v12, vcc, 0x168000, v12
	s_nop 0
	s_nop 0
	v_addc_co_u32_e32 v13, vcc, 0, v13, vcc
	flat_load_dword v150, v[14:15]
	flat_load_dword v151, v[16:17]
	flat_load_dword v152, v[18:19]
	flat_load_dword v153, v[20:21]
	flat_load_dword v154, v[22:23]
	flat_load_dword v155, v[24:25]
	flat_load_dword v156, v[26:27]
	flat_load_dword v157, v[28:29]
	flat_load_dword v158, v[12:13]
	flat_load_dword v159, v[8:9]
	v_add_co_u32_e32 v10, vcc, s1, v10
	v_lshl_add_u64 v[8:9], v[4:5], 0, s[16:17]
	s_nop 0
	v_addc_co_u32_e32 v11, vcc, 0, v11, vcc
	v_add_co_u32_e32 v12, vcc, s4, v8
	s_add_u32 s16, s16, 0x800
	s_nop 0
	v_addc_co_u32_e32 v13, vcc, 0, v9, vcc
	v_add_co_u32_e32 v14, vcc, s5, v8
	s_addc_u32 s17, s17, 0
	s_nop 0
	v_addc_co_u32_e32 v15, vcc, 0, v9, vcc
	v_add_co_u32_e32 v16, vcc, s18, v8
	s_nop 0
	s_nop 0
	v_addc_co_u32_e32 v17, vcc, 0, v9, vcc
	s_nop 0
	v_add_co_u32_e32 v18, vcc, s19, v8
	s_nop 0
	s_nop 0
	v_addc_co_u32_e32 v19, vcc, 0, v9, vcc
	s_nop 0
	v_add_co_u32_e32 v20, vcc, s20, v8
	s_nop 0
	s_nop 0
	v_addc_co_u32_e32 v21, vcc, 0, v9, vcc
	s_nop 0
	v_add_co_u32_e32 v22, vcc, s21, v8
	s_nop 0
	s_nop 0
	v_addc_co_u32_e32 v23, vcc, 0, v9, vcc
	s_nop 0
	v_add_co_u32_e32 v24, vcc, s22, v8
	s_nop 0
	s_nop 0
	v_addc_co_u32_e32 v25, vcc, 0, v9, vcc
	s_nop 0
	v_add_co_u32_e32 v8, vcc, s23, v8
	s_nop 0
	s_nop 0
	v_addc_co_u32_e32 v9, vcc, 0, v9, vcc
	flat_load_dword v160, v[10:11]
	flat_load_dword v161, v[12:13]
	flat_load_dword v162, v[14:15]
	flat_load_dword v163, v[16:17]
	flat_load_dword v164, v[18:19]
	flat_load_dword v165, v[20:21]
	flat_load_dword v166, v[22:23]
	flat_load_dword v167, v[24:25]
	flat_load_dword v168, v[8:9]
	v_cmp_lt_i32_e32 vcc, s24, v7
	s_or_b64 s[14:15], vcc, s[14:15]
	v_lshl_add_u64 v[10:11], v[94:95], 0, s[16:17]
	v_lshl_add_u64 v[12:13], v[2:3], 0, s[16:17]
	flat_load_dword v170, v[10:11]
	flat_load_dword v171, v[12:13]
	v_add_co_u32_e32 v10, vcc, 0x30000, v12
	v_lshl_add_u64 v[8:9], v[100:101], 0, s[16:17]
	s_nop 0
	v_addc_co_u32_e32 v11, vcc, 0, v13, vcc
	v_add_co_u32_e32 v14, vcc, 0x60000, v12
	flat_load_dword v172, v[10:11]
	s_nop 0
	v_addc_co_u32_e32 v15, vcc, 0, v13, vcc
	v_add_co_u32_e32 v10, vcc, 0x90000, v12
	v_add_u32_e32 v7, 0x200, v7
	s_nop 0
	v_addc_co_u32_e32 v11, vcc, 0, v13, vcc
	v_add_co_u32_e32 v16, vcc, 0xc0000, v12
	flat_load_dword v173, v[14:15]
	flat_load_dword v174, v[10:11]
	v_addc_co_u32_e32 v17, vcc, 0, v13, vcc
	v_add_co_u32_e32 v10, vcc, 0xf0000, v12
	s_nop 0
	s_nop 0
	v_addc_co_u32_e32 v11, vcc, 0, v13, vcc
	v_add_co_u32_e32 v14, vcc, 0x120000, v12
	flat_load_dword v175, v[16:17]
	flat_load_dword v176, v[10:11]
	v_addc_co_u32_e32 v15, vcc, 0, v13, vcc
; __device__ __forceinline__ float mod_val(const float* modp, const float* adab, int l, int b, int j) {
;     float s = adab[l * 3072 + j];
; #pragma unroll
;     for (int kc = 0; kc < KS; ++kc) s += modp[((size_t)(kc * 2 + l) * 8 + b) * 3072 + j];
;     return s;
; __device__ __forceinline__ void p3b_rows(const Args& A, char* lds, int G) {
;     ...
;         for (int col = tid; col < 1024; col += NTHR) { mv[col] = A.in[I_POSTG][col] * mod_val(modp, A.in[I_ADAB], 0, b, 2048 + col);
;             mv[1024 + col] = A.in[I_PREG][1024 + col] * (1.f + mod_val(modp, A.in[I_ADAB], 1, b, 1024 + col)); mv[2048 + col] = mod_val(modp, A.in[I_ADAB], 1, b, col); }
	v_add_co_u32_e32 v10, vcc, 0x150000, v12
	s_nop 0
	s_nop 0
	v_addc_co_u32_e32 v11, vcc, 0, v13, vcc
	flat_load_dword v177, v[14:15]
	flat_load_dword v178, v[10:11]
	flat_load_dword v179, v[8:9]
	v_lshl_add_u64 v[10:11], v[98:99], 0, s[16:17]
	v_add_co_u32_e32 v14, vcc, 0x4000, v10
	v_lshl_add_u64 v[12:13], v[0:1], 0, s[16:17]
	s_nop 0
	v_addc_co_u32_e32 v15, vcc, 0, v11, vcc
	v_add_co_u32_e32 v16, vcc, 0x18000, v12
	s_nop 0
	s_nop 0
	v_addc_co_u32_e32 v17, vcc, 0, v13, vcc
	v_add_co_u32_e32 v18, vcc, 0x48000, v12
	s_nop 0
	s_nop 0
	v_addc_co_u32_e32 v19, vcc, 0, v13, vcc
	v_add_co_u32_e32 v20, vcc, 0x78000, v12
	v_lshl_add_u64 v[8:9], v[90:91], 0, s[16:17]
	s_nop 0
	v_addc_co_u32_e32 v21, vcc, 0, v13, vcc
	v_add_co_u32_e32 v22, vcc, 0xa8000, v12
	s_nop 0
	s_nop 0
	v_addc_co_u32_e32 v23, vcc, 0, v13, vcc
	v_add_co_u32_e32 v24, vcc, 0xd8000, v12
	s_nop 0
	s_nop 0
	v_addc_co_u32_e32 v25, vcc, 0, v13, vcc
	v_add_co_u32_e32 v26, vcc, 0x108000, v12
	s_nop 0
	s_nop 0
	v_addc_co_u32_e32 v27, vcc, 0, v13, vcc
	v_add_co_u32_e32 v28, vcc, 0x138000, v12
	s_nop 0
	s_nop 0
	v_addc_co_u32_e32 v29, vcc, 0, v13, vcc
	s_nop 0
	v_add_co_u32_e32 v12, vcc, 0x168000, v12
	s_nop 0
	s_nop 0
	v_addc_co_u32_e32 v13, vcc, 0, v13, vcc
	flat_load_dword v180, v[14:15]
	flat_load_dword v181, v[16:17]
	flat_load_dword v182, v[18:19]
	flat_load_dword v183, v[20:21]
	flat_load_dword v184, v[22:23]
	flat_load_dword v185, v[24:25]
	flat_load_dword v186, v[26:27]
	flat_load_dword v187, v[28:29]
	flat_load_dword v188, v[12:13]
	flat_load_dword v189, v[8:9]
	v_add_co_u32_e32 v10, vcc, s1, v10
	v_lshl_add_u64 v[8:9], v[4:5], 0, s[16:17]
	s_nop 0
	v_addc_co_u32_e32 v11, vcc, 0, v11, vcc
	v_add_co_u32_e32 v12, vcc, s4, v8
	s_add_u32 s16, s16, 0x800
	s_nop 0
	v_addc_co_u32_e32 v13, vcc, 0, v9, vcc
	v_add_co_u32_e32 v14, vcc, s5, v8
	s_addc_u32 s17, s17, 0
	s_nop 0
	v_addc_co_u32_e32 v15, vcc, 0, v9, vcc
	v_add_co_u32_e32 v16, vcc, s18, v8
	s_nop 0
	s_nop 0
	v_addc_co_u32_e32 v17, vcc, 0, v9, vcc
	s_nop 0
	v_add_co_u32_e32 v18, vcc, s19, v8
	s_nop 0
	s_nop 0
	v_addc_co_u32_e32 v19, vcc, 0, v9, vcc
	s_nop 0
	v_add_co_u32_e32 v20, vcc, s20, v8
	s_nop 0
	s_nop 0
	v_addc_co_u32_e32 v21, vcc, 0, v9, vcc
	s_nop 0
	v_add_co_u32_e32 v22, vcc, s21, v8
	s_nop 0
	s_nop 0
	v_addc_co_u32_e32 v23, vcc, 0, v9, vcc
	s_nop 0
	v_add_co_u32_e32 v24, vcc, s22, v8
	s_nop 0
	s_nop 0
	v_addc_co_u32_e32 v25, vcc, 0, v9, vcc
	s_nop 0
	v_add_co_u32_e32 v8, vcc, s23, v8
	s_nop 0
	s_nop 0
	v_addc_co_u32_e32 v9, vcc, 0, v9, vcc
	flat_load_dword v190, v[10:11]
	flat_load_dword v191, v[12:13]
	flat_load_dword v192, v[14:15]
	flat_load_dword v193, v[16:17]
	flat_load_dword v194, v[18:19]
	flat_load_dword v195, v[20:21]
	flat_load_dword v196, v[22:23]
	flat_load_dword v197, v[24:25]
	flat_load_dword v198, v[8:9]
	v_cmp_lt_i32_e32 vcc, s24, v7
	s_or_b64 s[14:15], vcc, s[14:15]
	s_waitcnt vmcnt(0) lgkmcnt(0)
	v_add_f32_e32 v30, v30, v31
	v_add_f32_e32 v30, v30, v32
	v_add_f32_e32 v30, v30, v33
	v_add_f32_e32 v30, v30, v34
	v_add_f32_e32 v30, v30, v35
	v_add_f32_e32 v30, v30, v36
	v_add_f32_e32 v30, v30, v37
	v_add_f32_e32 v30, v30, v38
	v_mul_f32_e32 v30, v39, v30
	ds_write_b32 v6, v30
	v_add_f32_e32 v26, v150, v151
	v_add_f32_e32 v26, v26, v152
	v_add_f32_e32 v26, v26, v153
	v_add_f32_e32 v26, v26, v154
	v_add_f32_e32 v26, v26, v155
	v_add_f32_e32 v26, v26, v156
	v_add_f32_e32 v26, v26, v157
	v_add_f32_e32 v26, v26, v158
	v_add_f32_e32 v26, 1.0, v26
	v_mul_f32_e32 v26, v159, v26
	ds_write_b32 v6, v26 offset:4096
	v_add_f32_e32 v8, v160, v161
	v_add_f32_e32 v8, v8, v162
	v_add_f32_e32 v8, v8, v163
	v_add_f32_e32 v8, v8, v164
	v_add_f32_e32 v8, v8, v165
	v_add_f32_e32 v8, v8, v166
	v_add_f32_e32 v8, v8, v167
	v_add_f32_e32 v8, v8, v168
	ds_write_b32 v6, v8 offset:8192
	v_add_u32_e32 v6, 0x800, v6
	v_add_f32_e32 v170, v170, v171
	v_add_f32_e32 v170, v170, v172
	v_add_f32_e32 v170, v170, v173
	v_add_f32_e32 v170, v170, v174
	v_add_f32_e32 v170, v170, v175
	v_add_f32_e32 v170, v170, v176
	v_add_f32_e32 v170, v170, v177
	v_add_f32_e32 v170, v170, v178
	v_mul_f32_e32 v170, v179, v170
	ds_write_b32 v6, v170
	v_add_f32_e32 v26, v180, v181
	v_add_f32_e32 v26, v26, v182
	v_add_f32_e32 v26, v26, v183
	v_add_f32_e32 v26, v26, v184
	v_add_f32_e32 v26, v26, v185
	v_add_f32_e32 v26, v26, v186
	v_add_f32_e32 v26, v26, v187
	v_add_f32_e32 v26, v26, v188
	v_add_f32_e32 v26, 1.0, v26
	v_mul_f32_e32 v26, v189, v26
	ds_write_b32 v6, v26 offset:4096
	v_add_f32_e32 v8, v190, v191
	v_add_f32_e32 v8, v8, v192
	v_add_f32_e32 v8, v8, v193
	v_add_f32_e32 v8, v8, v194
	v_add_f32_e32 v8, v8, v195
	v_add_f32_e32 v8, v8, v196
	v_add_f32_e32 v8, v8, v197
	v_add_f32_e32 v8, v8, v198
	ds_write_b32 v6, v8 offset:8192
	v_add_u32_e32 v6, 0x800, v6

; __device__ __forceinline__ float mod_val(const float* modp, const float* adab, int l, int b, int j) {
;     float s = adab[l * 3072 + j];
; #pragma unroll
;     for (int kc = 0; kc < KS; ++kc) s += modp[((size_t)(kc * 2 + l) * 8 + b) * 3072 + j];
;     return s;
; __device__ __forceinline__ void p6b_rows(const Args& A, char* lds, int G) {
;     ...
;         for (int col = tid; col < 1024; col += NTHR) { mv[col] = A.in[I_POSTG][col] * mod_val(modp, A.in[I_ADAB], 0, b, 2048 + col); mv[1024 + col] = A.in[I_POSTG][1024 + col] * mod_val(modp, A.in[I_ADAB], 1, b, 2048 + col); }
.LBB0_1650:
	v_lshl_add_u64 v[6:7], v[74:75], 0, s[14:15]
	v_lshl_add_u64 v[8:9], v[0:1], 0, s[14:15]
	flat_load_dword v24, v[6:7]
	flat_load_dword v25, v[8:9]
	v_add_co_u32_e32 v6, vcc, 0x30000, v8
	v_lshl_add_u64 v[4:5], v[78:79], 0, s[14:15]
	s_nop 0
	v_addc_co_u32_e32 v7, vcc, 0, v9, vcc
	v_add_co_u32_e32 v10, vcc, 0x60000, v8
	flat_load_dword v26, v[6:7]
	s_nop 0
	v_addc_co_u32_e32 v11, vcc, 0, v9, vcc
	v_add_co_u32_e32 v6, vcc, 0x90000, v8
	v_add_u32_e32 v3, 0x200, v3
	s_nop 0
	v_addc_co_u32_e32 v7, vcc, 0, v9, vcc
	v_add_co_u32_e32 v12, vcc, 0xc0000, v8
	flat_load_dword v27, v[10:11]
	flat_load_dword v28, v[6:7]
	v_addc_co_u32_e32 v13, vcc, 0, v9, vcc
	v_add_co_u32_e32 v6, vcc, 0xf0000, v8
	s_nop 0
	s_nop 0
	v_addc_co_u32_e32 v7, vcc, 0, v9, vcc
	v_add_co_u32_e32 v10, vcc, 0x120000, v8
	flat_load_dword v29, v[12:13]
	flat_load_dword v30, v[6:7]
	v_addc_co_u32_e32 v11, vcc, 0, v9, vcc
	v_add_co_u32_e32 v6, vcc, 0x150000, v8
	s_nop 0
	s_nop 0
	v_addc_co_u32_e32 v7, vcc, 0, v9, vcc
	flat_load_dword v31, v[10:11]
	flat_load_dword v32, v[6:7]
	flat_load_dword v33, v[4:5]
	v_add_co_u32_e32 v4, vcc, 0x1000, v4
	v_lshl_add_u64 v[6:7], v[76:77], 0, s[14:15]
	s_nop 0
	v_addc_co_u32_e32 v5, vcc, 0, v5, vcc
	v_add_co_u32_e32 v10, vcc, 0x18000, v8
	s_nop 0
	s_nop 0
	v_addc_co_u32_e32 v11, vcc, 0, v9, vcc
	v_add_co_u32_e32 v12, vcc, 0x48000, v8
	s_nop 0
	s_nop 0
	v_addc_co_u32_e32 v13, vcc, 0, v9, vcc
	v_add_co_u32_e32 v14, vcc, 0x78000, v8
	s_add_u32 s14, s14, 0x800
	s_nop 0
	v_addc_co_u32_e32 v15, vcc, 0, v9, vcc
	v_add_co_u32_e32 v16, vcc, 0xa8000, v8
	s_addc_u32 s15, s15, 0
	s_nop 0
	v_addc_co_u32_e32 v17, vcc, 0, v9, vcc
	v_add_co_u32_e32 v18, vcc, 0xd8000, v8
	s_nop 0
	s_nop 0
	v_addc_co_u32_e32 v19, vcc, 0, v9, vcc
	v_add_co_u32_e32 v20, vcc, 0x108000, v8
	s_nop 0
	s_nop 0
	v_addc_co_u32_e32 v21, vcc, 0, v9, vcc
	s_nop 0
	v_add_co_u32_e32 v22, vcc, 0x138000, v8
	s_nop 0
	s_nop 0
	v_addc_co_u32_e32 v23, vcc, 0, v9, vcc
	s_nop 0
	v_add_co_u32_e32 v8, vcc, 0x168000, v8
	s_nop 0
	s_nop 0
	v_addc_co_u32_e32 v9, vcc, 0, v9, vcc
	flat_load_dword v160, v[6:7]
	flat_load_dword v161, v[10:11]
	flat_load_dword v162, v[12:13]
	flat_load_dword v163, v[14:15]
	flat_load_dword v164, v[16:17]
	flat_load_dword v165, v[18:19]
	flat_load_dword v166, v[20:21]
	flat_load_dword v167, v[22:23]
	flat_load_dword v168, v[8:9]
	flat_load_dword v169, v[4:5]
	v_cmp_lt_i32_e32 vcc, s11, v3
	s_or_b64 s[12:13], vcc, s[12:13]
	v_lshl_add_u64 v[6:7], v[74:75], 0, s[14:15]
	v_lshl_add_u64 v[8:9], v[0:1], 0, s[14:15]
	flat_load_dword v180, v[6:7]
	flat_load_dword v181, v[8:9]
	v_add_co_u32_e32 v6, vcc, 0x30000, v8
	v_lshl_add_u64 v[4:5], v[78:79], 0, s[14:15]
	s_nop 0
	v_addc_co_u32_e32 v7, vcc, 0, v9, vcc
	v_add_co_u32_e32 v10, vcc, 0x60000, v8
	flat_load_dword v182, v[6:7]
	s_nop 0
	v_addc_co_u32_e32 v11, vcc, 0, v9, vcc
	v_add_co_u32_e32 v6, vcc, 0x90000, v8
	v_add_u32_e32 v3, 0x200, v3
	s_nop 0
	v_addc_co_u32_e32 v7, vcc, 0, v9, vcc
	v_add_co_u32_e32 v12, vcc, 0xc0000, v8
	flat_load_dword v183, v[10:11]
	flat_load_dword v184, v[6:7]
	v_addc_co_u32_e32 v13, vcc, 0, v9, vcc
	v_add_co_u32_e32 v6, vcc, 0xf0000, v8
	s_nop 0
	s_nop 0
	v_addc_co_u32_e32 v7, vcc, 0, v9, vcc
	v_add_co_u32_e32 v10, vcc, 0x120000, v8
	flat_load_dword v185, v[12:13]
	flat_load_dword v186, v[6:7]
	v_addc_co_u32_e32 v11, vcc, 0, v9, vcc
	v_add_co_u32_e32 v6, vcc, 0x150000, v8
	s_nop 0
	s_nop 0
	v_addc_co_u32_e32 v7, vcc, 0, v9, vcc
	flat_load_dword v187, v[10:11]
	flat_load_dword v188, v[6:7]
	flat_load_dword v189, v[4:5]
	v_add_co_u32_e32 v4, vcc, 0x1000, v4
	v_lshl_add_u64 v[6:7], v[76:77], 0, s[14:15]
	s_nop 0
	v_addc_co_u32_e32 v5, vcc, 0, v5, vcc
	v_add_co_u32_e32 v10, vcc, 0x18000, v8
	s_nop 0
	s_nop 0
	v_addc_co_u32_e32 v11, vcc, 0, v9, vcc
	v_add_co_u32_e32 v12, vcc, 0x48000, v8
	s_nop 0
	s_nop 0
	v_addc_co_u32_e32 v13, vcc, 0, v9, vcc
	v_add_co_u32_e32 v14, vcc, 0x78000, v8
	s_add_u32 s14, s14, 0x800
	s_nop 0
	v_addc_co_u32_e32 v15, vcc, 0, v9, vcc
	v_add_co_u32_e32 v16, vcc, 0xa8000, v8
	s_addc_u32 s15, s15, 0
	s_nop 0
	v_addc_co_u32_e32 v17, vcc, 0, v9, vcc
	v_add_co_u32_e32 v18, vcc, 0xd8000, v8
	s_nop 0
	s_nop 0
	v_addc_co_u32_e32 v19, vcc, 0, v9, vcc
	v_add_co_u32_e32 v20, vcc, 0x108000, v8
	s_nop 0
	s_nop 0
	v_addc_co_u32_e32 v21, vcc, 0, v9, vcc
	s_nop 0
	v_add_co_u32_e32 v22, vcc, 0x138000, v8
	s_nop 0
	s_nop 0
	v_addc_co_u32_e32 v23, vcc, 0, v9, vcc
	s_nop 0
	v_add_co_u32_e32 v8, vcc, 0x168000, v8
	s_nop 0
	s_nop 0
	v_addc_co_u32_e32 v9, vcc, 0, v9, vcc
	flat_load_dword v190, v[6:7]
	flat_load_dword v191, v[10:11]
	flat_load_dword v192, v[12:13]
	flat_load_dword v193, v[14:15]
	flat_load_dword v194, v[16:17]
	flat_load_dword v195, v[18:19]
	flat_load_dword v196, v[20:21]
	flat_load_dword v197, v[22:23]
	flat_load_dword v198, v[8:9]
	flat_load_dword v199, v[4:5]
	v_cmp_lt_i32_e32 vcc, s11, v3
	s_or_b64 s[12:13], vcc, s[12:13]
	s_waitcnt vmcnt(0) lgkmcnt(0)
	v_add_f32_e32 v24, v24, v25
	v_add_f32_e32 v24, v24, v26
	v_add_f32_e32 v24, v24, v27
	v_add_f32_e32 v24, v24, v28
	v_add_f32_e32 v24, v24, v29
	v_add_f32_e32 v24, v24, v30
	v_add_f32_e32 v24, v24, v31
	v_add_f32_e32 v24, v24, v32
	v_mul_f32_e32 v24, v33, v24
	ds_write_b32 v2, v24
	v_add_f32_e32 v4, v160, v161
	v_add_f32_e32 v4, v4, v162
	v_add_f32_e32 v4, v4, v163
	v_add_f32_e32 v4, v4, v164
	v_add_f32_e32 v4, v4, v165
	v_add_f32_e32 v4, v4, v166
	v_add_f32_e32 v4, v4, v167
	v_add_f32_e32 v4, v4, v168
	v_mul_f32_e32 v4, v169, v4
	ds_write_b32 v2, v4 offset:4096
	v_add_u32_e32 v2, 0x800, v2
	v_add_f32_e32 v180, v180, v181
	v_add_f32_e32 v180, v180, v182
	v_add_f32_e32 v180, v180, v183
	v_add_f32_e32 v180, v180, v184
	v_add_f32_e32 v180, v180, v185
	v_add_f32_e32 v180, v180, v186
	v_add_f32_e32 v180, v180, v187
	v_add_f32_e32 v180, v180, v188
	v_mul_f32_e32 v180, v189, v180
	ds_write_b32 v2, v180
	v_add_f32_e32 v4, v190, v191
	v_add_f32_e32 v4, v4, v192
	v_add_f32_e32 v4, v4, v193
	v_add_f32_e32 v4, v4, v194
	v_add_f32_e32 v4, v4, v195
	v_add_f32_e32 v4, v4, v196
	v_add_f32_e32 v4, v4, v197
	v_add_f32_e32 v4, v4, v198
	v_mul_f32_e32 v4, v199, v4
	ds_write_b32 v2, v4 offset:4096
	v_add_u32_e32 v2, 0x800, v2
